# twin: P0 w_in transpose items with hand-written 8-row groups and scalar win_map decode (+ gains once per item), on top of v72 minus tgain
# speedup vs baseline: 1.0042x; 1.0042x over previous
; #define LAS __attribute__((address_space(3)))
; __device__ __forceinline__ unsigned cvt_pk_bf16(float lo, float hi) { unsigned r; asm volatile("v_cvt_pk_bf16_f32 %0, %1, %2" : "=v"(r) : "v"(lo), "v"(hi)); return r; }
; __device__ __forceinline__ int win_map(int n) {
;     if (n < 1024) { const int d = n & 63; return (n & ~63) + 2 * (d & 31) + (d >> 5); }
;     if (n < 1280) { const int q = n - 1024, d = q & 63; return 2048 + (q & ~63) + 2 * (d & 31) + (d >> 5); }
;     if (n < 1536) return 2304 + (n - 1280);
;     if (n < 2560) return 2560 + (n - 1536);
;     if (n < 3072) return 1024 + (n - 2560);
;     if (n < 3584) { const int ch = n - 3072; return 4608 + 256 * (ch >> 7) + (ch & 127); }
;     if (n < 4096) { const int ch = n - 3584; return 4608 + 256 * (ch >> 7) + 128 + (ch & 127); }
;     if (n < 4608) return 3584 + (n - 4096);
;     if (n < 5120) return 1536 + (n - 4608);
;     return 4096 + (n - 5120);
; }
; template <bool MAPIN>
; __device__ __forceinline__ void transpose_item(const float* W, int K, int N, bf16_t* WT, LAS float* scr, int item, int lane, const float* gk = nullptr) {
;     ...
;     for (int j = 0; j < 4; ++j) { const int n = (lane >> 3) + 8 * j; const LAS float* s = scr + (8 * c) * 33 + n;
;         f32x4 ga = (f32x4){1.f, 1.f, 1.f, 1.f}, gb = ga;
;         if (gk) { ga = *(const f32x4*)(gk + k0 + 8 * c); gb = *(const f32x4*)(gk + k0 + 8 * c + 4); }
;         u32x4 o; o.x = cvt_pk_bf16(s[0 * 33] * ga[0], s[1 * 33] * ga[1]); o.y = cvt_pk_bf16(s[2 * 33] * ga[2], s[3 * 33] * ga[3]); o.z = cvt_pk_bf16(s[4 * 33] * gb[0], s[5 * 33] * gb[1]); o.w = cvt_pk_bf16(s[6 * 33] * gb[2], s[7 * 33] * gb[3]);
;         const int nd = MAPIN ? win_map(n0 + n) : (n0 + n);
;         *(u32x4*)(WT + (size_t)nd * K + k0 + 8 * c) = o; }
.LBB0_123:
	s_or_b64 exec, exec, s[0:1]
	ds_read2_b32 v[38:39], v19 offset0:0 offset1:33
	ds_read2_b32 v[40:41], v19 offset0:66 offset1:99
	ds_read2_b32 v[42:43], v19 offset0:132 offset1:165
	ds_read2_b32 v[44:45], v19 offset0:198 offset1:231
	ds_read2_b32 v[46:47], v19 offset0:8 offset1:41
	ds_read2_b32 v[48:49], v19 offset0:74 offset1:107
	ds_read2_b32 v[50:51], v19 offset0:140 offset1:173
	ds_read2_b32 v[52:53], v19 offset0:206 offset1:239
	ds_read2_b32 v[54:55], v19 offset0:16 offset1:49
	ds_read2_b32 v[56:57], v19 offset0:82 offset1:115
	ds_read2_b32 v[58:59], v19 offset0:148 offset1:181
	ds_read2_b32 v[60:61], v19 offset0:214 offset1:247
	ds_read2_b32 v[62:63], v19 offset0:24 offset1:57
	ds_read2_b32 v[0:1], v19 offset0:90 offset1:123
	ds_read2_b32 v[2:3], v19 offset0:156 offset1:189
	ds_read2_b32 v[4:5], v19 offset0:222 offset1:255
	v_readfirstlane_b32 s18, v10
	v_readfirstlane_b32 s19, v36
	v_readfirstlane_b32 s20, v24
	s_cmpk_lt_u32 s19, 0x1e00
	s_cselect_b32 s22, s98, s37
	s_cselect_b32 s23, s99, s38
	s_lshl_b32 s21, s20, 1
	s_add_u32 s22, s22, s21
	s_addc_u32 s23, s23, 0
	s_mov_b32 s25, 0
	s_cmpk_lt_u32 s18, 0x500
	s_cbranch_scc0 .Ltw_lin
	s_mov_b32 s25, 1
	s_and_b32 s24, s18, 0xffffffc0
	s_bfe_u32 s26, s18, 0x10005
	s_add_u32 s24, s24, s26
	s_cmpk_lt_u32 s18, 0x400
	s_cbranch_scc1 .Ltw_go
	s_add_u32 s24, s24, 0x400
	s_branch .Ltw_go
.Ltw_lin:
	s_add_i32 s24, s18, 1024
	s_cmpk_lt_u32 s18, 0xa00
	s_cbranch_scc1 .Ltw_go
	s_add_i32 s24, s18, -1536
	s_cmpk_lt_u32 s18, 0xc00
	s_cbranch_scc1 .Ltw_go
	s_cmpk_lt_u32 s18, 0x1000
	s_cbranch_scc0 .Ltw_hi
	s_sub_u32 s26, s18, 0xc00
	s_and_b32 s27, s26, 0x1ff
	s_lshr_b32 s24, s27, 7
	s_lshl_b32 s24, s24, 8
	s_and_b32 s27, s27, 0x7f
	s_add_u32 s24, s24, s27
	s_add_u32 s24, s24, 0x1200
	s_lshr_b32 s26, s26, 9
	s_lshl_b32 s26, s26, 7
	s_add_u32 s24, s24, s26
	s_branch .Ltw_go
.Ltw_hi:
	s_add_i32 s24, s18, -512
	s_cmpk_lt_u32 s18, 0x1200
	s_cbranch_scc1 .Ltw_go
	s_add_i32 s24, s18, -3072
	s_cmpk_lt_u32 s18, 0x1400
	s_cbranch_scc1 .Ltw_go
	s_add_i32 s24, s18, -1024
.Ltw_go:
	s_lshl_b32 s21, s24, 12
	s_add_u32 s22, s22, s21
	s_addc_u32 s23, s23, 0
	s_add_i32 s26, s25, 12
	v_lshlrev_b32_e32 v126, s26, v17
	v_lshl_add_u32 v126, v18, 1, v126
	s_lshl_b32 s27, 0x8000, s25
	s_waitcnt vmcnt(0) lgkmcnt(0)
	v_pk_mul_f32 v[38:39], v[102:103], v[38:39]
	v_pk_mul_f32 v[40:41], v[104:105], v[40:41]
	v_pk_mul_f32 v[42:43], v[106:107], v[42:43]
	v_pk_mul_f32 v[44:45], v[108:109], v[44:45]
	v_cvt_pk_bf16_f32 v110, v38, v39
	v_cvt_pk_bf16_f32 v111, v40, v41
	v_cvt_pk_bf16_f32 v112, v42, v43
	v_cvt_pk_bf16_f32 v113, v44, v45
	global_store_dwordx4 v126, v[110:113], s[22:23]
	s_add_u32 s22, s22, s27
	s_addc_u32 s23, s23, 0
	v_pk_mul_f32 v[46:47], v[102:103], v[46:47]
	v_pk_mul_f32 v[48:49], v[104:105], v[48:49]
	v_pk_mul_f32 v[50:51], v[106:107], v[50:51]
	v_pk_mul_f32 v[52:53], v[108:109], v[52:53]
	v_cvt_pk_bf16_f32 v114, v46, v47
	v_cvt_pk_bf16_f32 v115, v48, v49
	v_cvt_pk_bf16_f32 v116, v50, v51
	v_cvt_pk_bf16_f32 v117, v52, v53
	global_store_dwordx4 v126, v[114:117], s[22:23]
	s_add_u32 s22, s22, s27
	s_addc_u32 s23, s23, 0
	v_pk_mul_f32 v[54:55], v[102:103], v[54:55]
	v_pk_mul_f32 v[56:57], v[104:105], v[56:57]
	v_pk_mul_f32 v[58:59], v[106:107], v[58:59]
	v_pk_mul_f32 v[60:61], v[108:109], v[60:61]
	v_cvt_pk_bf16_f32 v118, v54, v55
	v_cvt_pk_bf16_f32 v119, v56, v57
	v_cvt_pk_bf16_f32 v120, v58, v59
	v_cvt_pk_bf16_f32 v121, v60, v61
	global_store_dwordx4 v126, v[118:121], s[22:23]
	s_add_u32 s22, s22, s27
	s_addc_u32 s23, s23, 0
	v_pk_mul_f32 v[62:63], v[102:103], v[62:63]
	v_pk_mul_f32 v[0:1], v[104:105], v[0:1]
	v_pk_mul_f32 v[2:3], v[106:107], v[2:3]
	v_pk_mul_f32 v[4:5], v[108:109], v[4:5]
	v_cvt_pk_bf16_f32 v122, v62, v63
	v_cvt_pk_bf16_f32 v123, v0, v1
	v_cvt_pk_bf16_f32 v124, v2, v3
	v_cvt_pk_bf16_f32 v125, v4, v5
	global_store_dwordx4 v126, v[122:125], s[22:23]
	s_branch .LBB0_97
